# v79 plus retention silu(g) loads prefetched one chunk ahead (separate registers, copied at the loop top)
# baseline (speedup 1.0000x reference)
; #define LAS __attribute__((address_space(3)))
; __device__ __forceinline__ void retention_unit(LAS unsigned char* lds, const Ptrs& P, int b, int h, int tid) {
;     ...
;     const int lrow = tid >> 3, lseg = tid & 7, vrow0 = tid >> 4, vseg = tid & 15;
;     const size_t tok0 = (size_t)b * SEQ;
;     const bf16* gq = P.Q + (tok0 + lrow) * 256 + h * 64 + lseg * 8; const bf16* gk = P.K + (tok0 + lrow) * 256 + h * 64 + lseg * 8;
;     const bf16* gv = P.V + (tok0 + vrow0) * 512 + h * 128 + vseg * 8;
;     const bf16* gsl = P.SG + (tok0 + fr) * 512 + h * 128 + 16 * w + 4 * fq;
;     bf16* gol = P.RS + (tok0 + fr) * 1024 + h * 128 + 16 * w + 4 * fq;
;     v4u rq = __builtin_nontemporal_load((const v4u*)gq), rk = __builtin_nontemporal_load((const v4u*)gk), rv0 = __builtin_nontemporal_load((const v4u*)gv), rv1 = __builtin_nontemporal_load((const v4u*)(gv + 32 * 512));
;     const float dkey = ex2((float)(63 - lrow) * lg), dch = ex2(64.f * lg);
;     const f32x4 gng4 = *(const f32x4*)(P.gng + h * 128 + 16 * w + 4 * fq);
;     const int it3 = w >> 1;
;     float dqv[4]; f32x4 decv[2];
; #pragma unroll
;     for (int it = 0; it < 4; ++it) dqv[it] = ex2((float)(16 * it + fr + 1) * lg);
; #pragma unroll
;     for (int j2 = 0; j2 < 2; ++j2)
; #pragma unroll
;         for (int r = 0; r < 4; ++r) decv[j2][r] = ex2(__builtin_fabsf((float)((16 * it3 + fr) - (16 * ((w & 1) * 2 + j2) + 4 * fq + r))) * lg);
;     f32x4 op[4]; v2u sgr[4];
; #pragma unroll
;     for (int it = 0; it < 4; ++it) { op[it] = (f32x4){0.f, 0.f, 0.f, 0.f}; sgr[it] = (v2u){0u, 0u}; }
;     for (int n = 0; n <= 32; ++n) {
;         LAS unsigned char* bufc = lds + (n & 1) * RSET;
;         LAS bf16* Qs = (LAS bf16*)(bufc + ROFF_Q); LAS bf16* Ks = (LAS bf16*)(bufc + ROFF_K); LAS bf16* K2s = (LAS bf16*)(bufc + ROFF_K2); LAS bf16* Vs = (LAS bf16*)(bufc + ROFF_V);
;         if (n < 32) {
;             *(LAS v4u*)(Qs + lrow * S72 + lseg * 8) = rq; *(LAS v4u*)(Ks + lrow * S72 + lseg * 8) = rk;
;             v4u k2;
; #pragma unroll
;             for (int t = 0; t < 4; ++t) k2[t] = pk2(bflo(rk[t]) * dkey, bfhi(rk[t]) * dkey);
;             *(LAS v4u*)(K2s + lrow * S72 + lseg * 8) = k2;
;             *(LAS v4u*)(Vs + vrow0 * S144 + vseg * 8) = rv0; *(LAS v4u*)(Vs + (vrow0 + 32) * S144 + vseg * 8) = rv1;
;         }
;         if (n >= 1) {
; #pragma unroll
.LBB0_655:
	v_add_u32_e32 v1, 0x200, v1
	v_cmp_lt_u32_e32 vcc, s7, v1
	ds_write_b128 v0, v[180:183]
	s_or_b64 s[16:17], vcc, s[16:17]
	v_add_u32_e32 v0, 0x2000, v0
	s_andn2_b64 exec, exec, s[16:17]
	s_cbranch_execnz .LBB0_655
	s_or_b64 exec, exec, s[16:17]
	s_ashr_i32 s18, s86, 2
	s_ashr_i32 s19, s18, 31
	s_lshl_b64 s[16:17], s[18:19], 11
	v_mov_b32_e32 v1, s17
	v_or_b32_e32 v0, s16, v145
	v_lshlrev_b64 v[0:1], 9, v[0:1]
	v_lshl_add_u64 v[2:3], s[36:37], 0, v[0:1]
	s_lshl_b32 s4, s88, 7
	v_lshl_add_u64 v[0:1], s[48:49], 0, v[0:1]
	v_lshl_add_u64 v[2:3], v[2:3], 0, s[4:5]
	v_lshl_add_u64 v[0:1], v[0:1], 0, s[4:5]
	s_waitcnt vmcnt(2)
	v_lshl_add_u64 v[6:7], v[2:3], 0, v[72:73]
	v_lshl_add_u64 v[4:5], v[0:1], 0, v[72:73]
	v_mov_b32_e32 v1, s17
	v_or_b32_e32 v0, s16, v80
	global_load_dwordx4 v[8:11], v[6:7], off nt
	global_load_dwordx4 v[12:15], v[4:5], off nt
	v_lshlrev_b64 v[0:1], 10, v[0:1]
	s_lshl_b32 s90, s88, 8
	s_mov_b32 s91, s5
	v_lshl_add_u64 v[0:1], s[42:43], 0, v[0:1]
	v_lshl_add_u64 v[0:1], v[0:1], 0, s[90:91]
	v_lshl_add_u64 v[28:29], v[0:1], 0, v[84:85]
	v_add_co_u32_e32 v0, vcc, s21, v28
	s_and_b32 s93, s85, 3
	s_nop 0
	v_addc_co_u32_e32 v1, vcc, 0, v29, vcc
	global_load_dwordx4 v[16:19], v[28:29], off nt
	global_load_dwordx4 v[20:23], v[0:1], off nt
	s_lshr_b32 s87, s92, 6
	s_waitcnt lgkmcnt(0)
	v_mul_f32_e32 v0, s89, v147
	s_lshl_b32 s94, s88, 9
	s_lshl_b32 s91, s93, 7
	s_lshl_b32 s90, s93, 8
	s_lshl_b32 s88, s87, 4
	v_exp_f32_e32 v102, v0
	s_add_u32 s93, s50, s94
	s_addc_u32 s95, s51, 0
	s_and_b32 s94, s92, 0xffffffc0
	s_add_u32 s94, s93, s94
	s_addc_u32 s95, s95, 0
	global_load_dwordx4 v[0:3], v127, s[94:95]
	v_mov_b32_e32 v103, v102
	s_lshr_b32 s93, s92, 3
	s_lshr_b32 s92, s92, 5
	s_and_b32 s93, s93, 0x1ffffff0
	s_and_b32 s92, s92, 2
	s_waitcnt vmcnt(5)
	v_or_b32_e32 v24, s93, v144
	s_lshl_b32 s93, s92, 4
	v_or_b32_e32 v60, s93, v144
	v_mul_lo_u32 v62, v24, s20
	v_add_u32_e32 v176, v166, v62
	v_or_b32_e32 v25, s93, v146
	v_add_u32_e32 v26, v24, v152
	v_add_u32_e32 v27, v24, v153
	v_add_u32_e32 v30, v24, v154
	v_sub_u32_e32 v31, v24, v146
	v_sub_u32_e32 v24, v24, v25
	v_subrev_u32_e32 v25, s93, v26
	v_subrev_u32_e32 v32, s93, v27
	v_subrev_u32_e32 v33, s93, v30
	v_cvt_f32_i32_e32 v24, v24
	v_cvt_f32_i32_e32 v25, v25
	v_cvt_f32_i32_e32 v32, v32
	v_cvt_f32_i32_e32 v33, v33
	v_mul_f32_e64 v24, s89, |v24|
	v_mul_f32_e64 v25, s89, |v25|
	v_mul_f32_e64 v32, s89, |v32|
	v_mul_f32_e64 v33, s89, |v33|
	v_exp_f32_e32 v98, v24
	v_add_co_u32_e32 v24, vcc, s21, v6
	v_exp_f32_e32 v99, v25
	v_exp_f32_e32 v100, v32
	v_exp_f32_e32 v101, v33
	v_addc_co_u32_e32 v25, vcc, 0, v7, vcc
	s_xor_b32 s94, s93, -16
	v_add_u32_e32 v40, v156, v62
	s_lshl_b32 s93, s92, 5
	s_or_b32 s92, s92, 1
	v_add_u32_e32 v26, s94, v26
	v_add_u32_e32 v27, s94, v27
	v_add_u32_e32 v177, s93, v40
	v_lshl_or_b32 v61, s92, 4, v144
	v_cvt_f32_i32_e32 v26, v26
	v_cvt_f32_i32_e32 v27, v27
	v_add_co_u32_e32 v4, vcc, s21, v4
	s_waitcnt vmcnt(4)
	ds_write_b128 v164, v[8:11]
	s_waitcnt vmcnt(3)
	ds_write_b128 v164, v[12:15] offset:9216
	v_lshlrev_b32_e32 v8, 16, v12
	v_and_b32_e32 v9, 0xffff0000, v12
	v_lshlrev_b32_e32 v10, 16, v13
	v_and_b32_e32 v11, 0xffff0000, v13
	v_pk_mul_f32 v[8:9], v[102:103], v[8:9] op_sel_hi:[0,1]
	v_pk_mul_f32 v[10:11], v[102:103], v[10:11] op_sel_hi:[0,1]
	v_cvt_pk_bf16_f32 v8, v8, v9
	v_cvt_pk_bf16_f32 v9, v10, v11
	v_lshlrev_b32_e32 v10, 16, v14
	v_and_b32_e32 v11, 0xffff0000, v14
	v_lshlrev_b32_e32 v12, 16, v15
	v_and_b32_e32 v13, 0xffff0000, v15
	v_pk_mul_f32 v[10:11], v[102:103], v[10:11] op_sel_hi:[0,1]
	v_pk_mul_f32 v[12:13], v[102:103], v[12:13] op_sel_hi:[0,1]
	v_cvt_pk_bf16_f32 v10, v10, v11
	v_cvt_pk_bf16_f32 v11, v12, v13
	ds_write_b128 v164, v[8:11] offset:18432
	s_waitcnt vmcnt(2)
	ds_write_b128 v165, v[16:19] offset:27648
	s_waitcnt vmcnt(1)
	ds_write_b128 v165, v[20:23] offset:36864
	s_waitcnt lgkmcnt(0)
	s_barrier
	v_mad_u32_u24 v16, v60, s20, v166
	ds_read_b128 v[8:11], v16 offset:9216
	ds_read_b128 v[12:15], v176
	ds_read_b128 v[16:19], v16 offset:9280
	v_or_b32_e32 v20, s88, v144
	v_mul_lo_u32 v48, v20, s20
	ds_read_b128 v[20:23], v176 offset:64
	s_waitcnt lgkmcnt(2)
	v_mfma_f32_16x16x32_bf16 v[8:11], v[8:11], v[12:15], 0
	v_mul_f32_e64 v26, s89, |v26|
	v_mul_f32_e64 v27, s89, |v27|
	v_exp_f32_e32 v93, v26
	s_waitcnt lgkmcnt(0)
	v_mfma_f32_16x16x32_bf16 v[6:9], v[16:19], v[20:23], v[8:11]
	v_exp_f32_e32 v94, v27
	v_addc_co_u32_e32 v5, vcc, 0, v5, vcc
	s_nop 0
	v_mad_u32_u24 v10, v61, s20, v166
	v_add_u32_e32 v31, s94, v31
	s_nop 2
	v_pk_mul_f32 v[8:9], v[100:101], v[8:9]
	v_pk_mul_f32 v[6:7], v[98:99], v[6:7]
	v_add_u32_e32 v30, s94, v30
	v_cvt_pk_bf16_f32 v6, v6, v7
	v_cvt_pk_bf16_f32 v7, v8, v9
	ds_write_b64 v177, v[6:7]
	ds_read_b128 v[6:9], v10 offset:9216
	global_load_dwordx4 v[36:39], v[24:25], off nt
	s_nop 0
	global_load_dwordx4 v[24:27], v[4:5], off nt
	ds_read_b128 v[16:19], v10 offset:9280
	v_cvt_f32_i32_e32 v31, v31
	v_cvt_f32_i32_e32 v30, v30
	s_waitcnt lgkmcnt(1)
	v_mfma_f32_16x16x32_bf16 v[4:7], v[6:9], v[12:15], 0
	v_mul_f32_e64 v31, s89, |v31|
	v_mul_f32_e64 v30, s89, |v30|
	v_exp_f32_e32 v92, v31
	v_exp_f32_e32 v95, v30
	s_waitcnt lgkmcnt(0)
	v_mfma_f32_16x16x32_bf16 v[4:7], v[16:19], v[20:23], v[4:7]
	v_add_co_u32_e32 v10, vcc, s56, v28
	s_lshl_b32 s92, s92, 5
	s_nop 0
	v_addc_co_u32_e32 v11, vcc, 0, v29, vcc
	v_add_co_u32_e32 v8, vcc, s57, v28
	s_nop 2
	v_pk_mul_f32 v[6:7], v[94:95], v[6:7]
	v_pk_mul_f32 v[4:5], v[92:93], v[4:5]
	v_add_u32_e32 v142, s92, v40
	v_cvt_pk_bf16_f32 v4, v4, v5
	v_cvt_pk_bf16_f32 v5, v6, v7
	v_addc_co_u32_e32 v9, vcc, 0, v29, vcc
	global_load_dwordx4 v[28:31], v[10:11], off nt
	global_load_dwordx4 v[32:35], v[8:9], off nt
	ds_write_b64 v142, v[4:5]
	v_add_u32_e32 v137, v161, v48
	s_waitcnt lgkmcnt(0)
	s_barrier
; #define LAS __attribute__((address_space(3)))
; __device__ __forceinline__ unsigned pk2(float lo, float hi) { return pg8::cvt_pk_bf16(lo, hi); }
; __device__ __forceinline__ f32x4 mfma16(bf16x8 a, bf16x8 b, f32x4 c) { return __builtin_amdgcn_mfma_f32_16x16x32_bf16(a, b, c, 0, 0, 0); }
; __device__ __forceinline__ void retention_unit(LAS unsigned char* lds, const Ptrs& P, int b, int h, int tid) {
;     ...
;         if (n < 32) {
;             f32x4 o[4]; bf16x8 bst[2], bv[2];
; #pragma unroll
;             for (int ks = 0; ks < 2; ++ks) { bst[ks] = *(const LAS bf16x8*)(St + (16 * w + fr) * S72 + 32 * ks + 8 * fq); bv[ks] = tr_frag(bufc + ROFF_V, S144 * 2, w, ks, fq, fr); }
; #pragma unroll
;             for (int it = 0; it < 4; ++it) { o[it] = (f32x4){0.f, 0.f, 0.f, 0.f};
; #pragma unroll
;                 for (int ks = 0; ks < 2; ++ks) { const bf16x8 qf = *(const LAS bf16x8*)(Qs + (16 * it + fr) * S72 + 32 * ks + 8 * fq); o[it] = mfma16(bst[ks], qf, o[it]); }
;                 o[it] = o[it] * dqv[it];
; #pragma unroll
;                 for (int ks = 0; ks < 2; ++ks) { const bf16x8 sf = *(const LAS bf16x8*)(Ss + (16 * it + fr) * S72 + 32 * ks + 8 * fq); o[it] = mfma16(bv[ks], sf, o[it]); }
;             }
; #pragma unroll
;             for (int dt = 0; dt < 4; ++dt) { st[dt] = st[dt] * dch;
; #pragma unroll
;                 for (int ks = 0; ks < 2; ++ks) { const bf16x8 kf = tr_frag(bufc + ROFF_K2, S72 * 2, dt, ks, fq, fr); st[dt] = mfma16(kf, bv[ks], st[dt]); }
;                 v2u pw; pw.x = pk2(st[dt][0], st[dt][1]); pw.y = pk2(st[dt][2], st[dt][3]);
;                 *(LAS v2u*)(St + (16 * w + fr) * S72 + 16 * dt + 4 * fq) = pw; }
; #pragma unroll
;             for (int it = 0; it < 4; ++it) { const f32x4 v = o[it]; typedef float f32x2 __attribute__((ext_vector_type(2)));
;                 *(LAS f32x2*)(part + ((16 * it + fr) * 32 + w * 4 + fq) * 2) = (f32x2){(v[0] + v[1]) + (v[2] + v[3]), (v[0] * v[0] + v[1] * v[1]) + (v[2] * v[2] + v[3] * v[3])};
;                 op[it] = v; }
	ds_read_b128 v[4:7], v137
	ds_read_b128 v[8:11], v137 offset:64
	ds_read_b128 v[12:15], v128
	v_mul_f32_e32 v16, s89, v148
	v_exp_f32_e32 v90, v16
	ds_read_b128 v[16:19], v128 offset:64
	s_waitcnt lgkmcnt(1)
	v_mfma_f32_16x16x32_bf16 v[12:15], v[4:7], v[12:15], 0
	s_lshl_b32 s87, s87, 5
	v_add3_u32 v40, v167, s87, v168
	ds_read_b64_tr_b16 v[52:53], v40 offset:27648
	ds_read_b64_tr_b16 v[54:55], v40 offset:28800
	ds_read_b64_tr_b16 v[58:59], v40 offset:38016
	s_waitcnt lgkmcnt(3)
	v_mfma_f32_16x16x32_bf16 v[12:15], v[8:11], v[16:19], v[12:15]
	ds_read_b128 v[16:19], v129
	ds_read_b64_tr_b16 v[56:57], v40 offset:36864
	v_mov_b32_e32 v91, v90
	ds_read_b128 v[20:23], v129 offset:64
	v_add_u32_e32 v132, v157, v48
	s_nop 2
	v_pk_mul_f32 v[14:15], v[90:91], v[14:15] op_sel_hi:[0,1]
	v_pk_mul_f32 v[12:13], v[90:91], v[12:13] op_sel_hi:[0,1]
	v_mul_f32_e32 v75, s89, v151
	v_exp_f32_e32 v88, v75
	s_waitcnt lgkmcnt(2)
	v_mfma_f32_16x16x32_bf16 v[12:15], v[52:55], v[16:19], v[12:15]
	s_lshl_b64 s[92:93], s[18:19], 20
	v_add_u32_e32 v133, s87, v172
	v_mov_b32_e32 v89, v88
	s_waitcnt lgkmcnt(0)
	v_mfma_f32_16x16x32_bf16 v[40:43], v[56:59], v[20:23], v[12:15]
	s_nop 2
	ds_read_b128 v[12:15], v128 offset:2304
	ds_read_b128 v[16:19], v128 offset:2368
	v_mul_f32_e32 v20, s89, v149
	v_exp_f32_e32 v78, v20
	s_waitcnt lgkmcnt(1)
	v_mfma_f32_16x16x32_bf16 v[12:15], v[4:7], v[12:15], 0
	ds_read_b128 v[20:23], v129 offset:2368
	v_mov_b32_e32 v79, v78
	s_or_b32 s92, s92, s91
	s_waitcnt lgkmcnt(1)
	v_mfma_f32_16x16x32_bf16 v[12:15], v[8:11], v[16:19], v[12:15]
	ds_read_b128 v[16:19], v129 offset:2304
	v_add_u32_e32 v134, s87, v173
	v_add_u32_e32 v135, s87, v174
	v_mul_u32_u24_e32 v179, 0x90, v60
	v_mul_u32_u24_e32 v178, 0x90, v61
	s_nop 2
	v_pk_mul_f32 v[14:15], v[78:79], v[14:15] op_sel_hi:[0,1]
	v_pk_mul_f32 v[12:13], v[78:79], v[12:13] op_sel_hi:[0,1]
	v_mov_b32_e32 v108, v90
	v_mov_b32_e32 v109, v90
	s_waitcnt lgkmcnt(0)
	v_mfma_f32_16x16x32_bf16 v[12:15], v[52:55], v[16:19], v[12:15]
	ds_read_b128 v[16:19], v128 offset:4608
	v_mov_b32_e32 v96, v88
	v_mov_b32_e32 v97, v88
	v_mfma_f32_16x16x32_bf16 v[44:47], v[56:59], v[20:23], v[12:15]
	v_mul_f32_e32 v21, s89, v150
	v_mul_f32_e32 v20, s89, v126
	v_exp_f32_e32 v86, v21
	s_nop 0
	ds_read_b128 v[12:15], v128 offset:4672
	s_waitcnt lgkmcnt(1)
	v_mfma_f32_16x16x32_bf16 v[16:19], v[4:7], v[16:19], 0
	v_exp_f32_e32 v74, v20
	v_mov_b32_e32 v87, v86
	s_mov_b32 s89, 0
	s_waitcnt lgkmcnt(0)
	v_mfma_f32_16x16x32_bf16 v[12:15], v[8:11], v[12:15], v[16:19]
	v_mul_f32_e32 v110, 0, v74
	v_mov_b32_e32 v111, v110
	v_mov_b32_e32 v112, v110
	ds_read_b128 v[16:19], v129 offset:4608
	ds_read_b64_tr_b16 v[20:21], v130 offset:18432
	ds_read_b64_tr_b16 v[22:23], v130 offset:19008
	ds_read_b128 v[48:51], v129 offset:4672
	s_nop 0
	v_pk_mul_f32 v[14:15], v[86:87], v[14:15] op_sel_hi:[0,1]
	v_pk_mul_f32 v[12:13], v[86:87], v[12:13] op_sel_hi:[0,1]
	v_mov_b32_e32 v113, v110
	v_mov_b32_e32 v76, v74
	s_waitcnt lgkmcnt(3)
	v_mfma_f32_16x16x32_bf16 v[12:15], v[52:55], v[16:19], v[12:15]
	ds_read_b64_tr_b16 v[16:17], v130 offset:23040
	ds_read_b64_tr_b16 v[18:19], v130 offset:23616
	ds_read_b128 v[104:107], v128 offset:6912
	ds_read_b128 v[114:117], v128 offset:6976
	ds_read_b128 v[118:121], v129 offset:6912
	ds_read_b128 v[138:141], v129 offset:6976
	v_mov_b32_e32 v77, v74
	s_waitcnt lgkmcnt(7)
	v_mfma_f32_16x16x32_bf16 v[20:23], v[20:23], v[52:55], v[110:113]
	v_add_u32_e32 v136, s87, v175
	s_waitcnt lgkmcnt(4)
	v_mfma_f32_16x16x32_bf16 v[16:19], v[16:19], v[56:59], v[20:23]
	v_mfma_f32_16x16x32_bf16 v[48:51], v[56:59], v[48:51], v[12:15]
	s_waitcnt lgkmcnt(3)
	v_mfma_f32_16x16x32_bf16 v[4:7], v[4:7], v[104:107], 0
	s_nop 4
	v_cvt_pk_bf16_f32 v20, v16, v17
	v_cvt_pk_bf16_f32 v21, v18, v19
	ds_write_b64 v132, v[20:21]
	ds_read_b64_tr_b16 v[20:21], v130 offset:18464
	ds_read_b64_tr_b16 v[22:23], v130 offset:19040
	ds_read_b64_tr_b16 v[12:13], v130 offset:23072
	ds_read_b64_tr_b16 v[14:15], v130 offset:23648
	s_waitcnt lgkmcnt(2)
	v_mfma_f32_16x16x32_bf16 v[20:23], v[20:23], v[52:55], v[110:113]
	s_waitcnt lgkmcnt(0)
	v_mfma_f32_16x16x32_bf16 v[12:15], v[12:15], v[56:59], v[20:23]
	v_mfma_f32_16x16x32_bf16 v[4:7], v[8:11], v[114:117], v[4:7]
	s_nop 6
	v_cvt_pk_bf16_f32 v20, v12, v13
	v_cvt_pk_bf16_f32 v21, v14, v15
	ds_write_b64 v132, v[20:21] offset:32
	ds_read_b64_tr_b16 v[20:21], v130 offset:18496
	ds_read_b64_tr_b16 v[22:23], v130 offset:19072
	ds_read_b64_tr_b16 v[104:105], v130 offset:23104
	ds_read_b64_tr_b16 v[106:107], v130 offset:23680
	s_waitcnt lgkmcnt(2)
	v_mfma_f32_16x16x32_bf16 v[8:11], v[20:23], v[52:55], v[110:113]
	v_mul_f32_e64 v6, v88, v6
	v_mul_f32_e64 v7, v88, v7
	v_pk_mul_f32 v[4:5], v[88:89], v[4:5] op_sel_hi:[0,1]
	s_waitcnt lgkmcnt(0)
	v_mfma_f32_16x16x32_bf16 v[8:11], v[104:107], v[56:59], v[8:11]
	v_mov_b32_e32 v106, v78
	v_mov_b32_e32 v107, v78
	v_mov_b32_e32 v104, v86
	v_mfma_f32_16x16x32_bf16 v[4:7], v[52:55], v[118:121], v[4:7]
	v_mov_b32_e32 v105, v86
	s_nop 2
	v_cvt_pk_bf16_f32 v20, v8, v9
	v_cvt_pk_bf16_f32 v21, v10, v11
	ds_write_b64 v132, v[20:21] offset:64
	ds_read_b64_tr_b16 v[114:115], v130 offset:18528
	ds_read_b64_tr_b16 v[116:117], v130 offset:19104
	ds_read_b64_tr_b16 v[118:119], v130 offset:23136
	ds_read_b64_tr_b16 v[120:121], v130 offset:23712
	v_mfma_f32_16x16x32_bf16 v[20:23], v[56:59], v[138:141], v[4:7]
	s_waitcnt lgkmcnt(2)
	v_mfma_f32_16x16x32_bf16 v[4:7], v[114:117], v[52:55], v[110:113]
	v_mul_f32_e32 v55, v41, v41
	v_mov_b32_e32 v54, v41
	s_waitcnt lgkmcnt(0)
; __device__ __forceinline__ void retention_unit(LAS unsigned char* lds, const Ptrs& P, int b, int h, int tid) {
;     ...
;             for (int it = 0; it < 4; ++it) sgr[it] = __builtin_nontemporal_load((const v2u*)(gsl + ((size_t)(n - 1) * 64 + 16 * it) * 512));
;         }
;         LBAR();
;         if (n + 1 < 32) { const size_t o4 = (size_t)(n + 1) * 64;
;             rq = __builtin_nontemporal_load((const v4u*)(gq + o4 * 256)); rk = __builtin_nontemporal_load((const v4u*)(gk + o4 * 256)); rv0 = __builtin_nontemporal_load((const v4u*)(gv + o4 * 512)); rv1 = __builtin_nontemporal_load((const v4u*)(gv + (o4 + 32) * 512)); }
;         if (n >= 1) {
;             const int row = tid >> 3, sub = tid & 7;
;             const f32x4 pa = *(const LAS f32x4*)(part + (row * 32 + sub * 4) * 2), pb = *(const LAS f32x4*)(part + (row * 32 + sub * 4) * 2 + 4);
;             float s1 = (pa[0] + pa[2]) + (pb[0] + pb[2]), s2 = (pa[1] + pa[3]) + (pb[1] + pb[3]);
; #pragma unroll
;             for (int x = 1; x < 8; x <<= 1) { s1 += __shfl_xor(s1, x); s2 += __shfl_xor(s2, x); }
;             if (sub == 0) { const float mean = s1 * (1.f / 128.f); float var = s2 * (1.f / 128.f) - mean * mean; var = var < 0.f ? 0.f : var;
;                 stat[row * 2] = mean; stat[row * 2 + 1] = __builtin_amdgcn_rsqf(var + 1e-5f); }
;         }
;         if (n < 32) {
; #pragma unroll
;             for (int j2 = 0; j2 < 2; ++j2) {
;                 const int jt = (w & 1) * 2 + j2; f32x4 a4 = (f32x4){0.f, 0.f, 0.f, 0.f};
; #pragma unroll
;                 for (int ks = 0; ks < 2; ++ks) {
;                     const bf16x8 qf = *(const LAS bf16x8*)(Qs + (16 * it3 + fr) * S72 + 32 * ks + 8 * fq), kf = *(const LAS bf16x8*)(Ks + (16 * jt + fr) * S72 + 32 * ks + 8 * fq);
;                     a4 = mfma16(kf, qf, a4); }
;                 a4 = a4 * decv[j2];
;                 v2u pw; pw.x = pk2(a4[0], a4[1]); pw.y = pk2(a4[2], a4[3]);
;                 *(LAS v2u*)(Ss + (16 * it3 + fr) * S72 + 16 * jt + 4 * fq) = pw;
;             }
;         }
;     ...
;             for (int it = 0; it < 4; ++it) { const f32x4 v = o[it]; typedef float f32x2 __attribute__((ext_vector_type(2)));
;                 *(LAS f32x2*)(part + ((16 * it + fr) * 32 + w * 4 + fq) * 2) = (f32x2){(v[0] + v[1]) + (v[2] + v[3]), (v[0] * v[0] + v[1] * v[1]) + (v[2] * v[2] + v[3] * v[3])};
;                 op[it] = v; }
	v_mfma_f32_16x16x32_bf16 v[4:7], v[118:121], v[56:59], v[4:7]
	v_mul_f32_e32 v57, v42, v42
	v_mul_f32_e32 v59, v43, v43
	v_mov_b32_e32 v56, v42
	v_mov_b32_e32 v58, v43
	v_lshl_add_u64 v[110:111], s[92:93], 0, v[64:65]
	s_nop 2
	v_cvt_pk_bf16_f32 v52, v4, v5
	v_cvt_pk_bf16_f32 v53, v6, v7
	ds_write_b64 v132, v[52:53] offset:96
	v_mul_f32_e32 v53, v40, v40
	v_mov_b32_e32 v52, v40
	v_pk_add_f32 v[52:53], v[52:53], v[54:55]
	v_pk_add_f32 v[54:55], v[56:57], v[58:59]
	v_mul_f32_e32 v57, v46, v46
	v_pk_add_f32 v[52:53], v[52:53], v[54:55]
	ds_write_b64 v133, v[52:53]
	v_mul_f32_e32 v53, v44, v44
	v_mul_f32_e32 v55, v45, v45
	v_mul_f32_e32 v59, v47, v47
	v_mov_b32_e32 v52, v44
	v_mov_b32_e32 v54, v45
	v_mov_b32_e32 v56, v46
	v_mov_b32_e32 v58, v47
	s_lshl_b64 s[92:93], s[18:19], 21
	v_pk_add_f32 v[52:53], v[52:53], v[54:55]
	v_pk_add_f32 v[54:55], v[56:57], v[58:59]
	s_or_b32 s94, s92, s90
	s_lshl_b64 s[18:19], s[18:19], 22
	v_pk_add_f32 v[52:53], v[52:53], v[54:55]
	s_add_u32 s90, s87, s90
	ds_write_b64 v134, v[52:53]
	v_mul_f32_e32 v53, v48, v48
	v_mul_f32_e32 v55, v49, v49
	v_mul_f32_e32 v57, v50, v50
	v_mul_f32_e32 v59, v51, v51
	v_mov_b32_e32 v52, v48
	v_mov_b32_e32 v54, v49
	v_mov_b32_e32 v56, v50
	v_mov_b32_e32 v58, v51
	s_addc_u32 s91, 0, 0
	v_pk_add_f32 v[52:53], v[52:53], v[54:55]
	v_pk_add_f32 v[54:55], v[56:57], v[58:59]
	s_add_u32 s18, s90, s18
	v_pk_add_f32 v[52:53], v[52:53], v[54:55]
	s_addc_u32 s19, s91, s19
	ds_write_b64 v135, v[52:53]
	v_mul_f32_e32 v53, v20, v20
	v_mul_f32_e32 v55, v21, v21
	v_mul_f32_e32 v57, v22, v22
	v_mul_f32_e32 v59, v23, v23
	v_mov_b32_e32 v52, v20
	v_mov_b32_e32 v54, v21
	v_mov_b32_e32 v56, v22
	v_mov_b32_e32 v58, v23
	v_lshl_add_u64 v[114:115], s[18:19], 0, v[68:69]
	s_add_u32 s18, s90, s92
	v_pk_add_f32 v[52:53], v[52:53], v[54:55]
	v_pk_add_f32 v[54:55], v[56:57], v[58:59]
	s_mov_b32 s95, s93
	s_addc_u32 s19, s91, s93
	v_pk_add_f32 v[52:53], v[52:53], v[54:55]
	v_lshl_add_u64 v[112:113], s[94:95], 0, v[66:67]
	v_lshl_add_u64 v[116:117], s[18:19], 0, v[70:71]
	ds_write_b64 v136, v[52:53]
	v_lshl_add_u64 v[184:185], s[26:27], 0, v[116:117]
	v_add_co_u32_e32 v186, vcc, s58, v184
	s_nop 1
	v_addc_co_u32_e32 v187, vcc, 0, v185, vcc
	v_add_co_u32_e32 v188, vcc, s59, v184
	s_nop 1
	v_addc_co_u32_e32 v189, vcc, 0, v185, vcc
	v_add_co_u32_e32 v190, vcc, s60, v184
	s_nop 1
	v_addc_co_u32_e32 v191, vcc, 0, v185, vcc
	v_add_co_u32_e32 v192, vcc, s61, v184
	s_nop 1
	v_addc_co_u32_e32 v193, vcc, 0, v185, vcc
	global_load_dwordx2 v[252:253], v[186:187], off nt
	global_load_dwordx2 v[254:255], v[188:189], off nt
	global_load_dwordx2 v[248:249], v[190:191], off nt
	global_load_dwordx2 v[214:215], v[192:193], off nt
	s_waitcnt vmcnt(0)
	s_branch .LBB0_658
.LBB0_657:
	s_or_b64 exec, exec, s[18:19]
	v_lshl_add_u32 v60, v155, 1, s90
	s_waitcnt lgkmcnt(0)
	v_add_u32_e32 v60, v60, v178
	v_and_b32_e32 v61, 0xffff0000, v54
	v_add_u32_e32 v75, 0, v160
	v_add_u32_e32 v143, 0x21400, v75
	v_lshl_add_u64 v[120:121], s[26:27], 0, v[114:115]
	v_add3_u32 v204, s90, v82, v169
	s_waitcnt lgkmcnt(1)
	v_mfma_f32_16x16x32_bf16 v[56:59], v[216:219], v[188:191], 0
	s_add_i32 s18, s90, s87
	v_lshlrev_b32_e32 v200, 16, v122
	v_and_b32_e32 v201, 0xffff0000, v122
	s_waitcnt lgkmcnt(0)
	v_mfma_f32_16x16x32_bf16 v[56:59], v[220:223], v[192:195], v[56:59]
	v_lshlrev_b32_e32 v122, 16, v123
	v_and_b32_e32 v123, 0xffff0000, v123
	v_add3_u32 v212, s90, v162, v170
	v_mov_b32_e32 v75, v74
	v_pk_mul_f32 v[18:19], v[74:75], v[18:19]
	s_nop 2
	v_pk_mul_f32 v[58:59], v[100:101], v[58:59]
	v_pk_mul_f32 v[56:57], v[98:99], v[56:57]
	v_pk_mul_f32 v[16:17], v[76:77], v[16:17]
	v_cvt_pk_bf16_f32 v56, v56, v57
	v_cvt_pk_bf16_f32 v57, v58, v59
	ds_write_b64 v177, v[56:57]
	ds_read_b128 v[56:59], v60 offset:9216
	ds_read_b128 v[184:187], v60 offset:9280
	ds_read_b128 v[216:219], v204
	ds_read_b128 v[220:223], v204 offset:64
	ds_read_b128 v[224:227], v204 offset:2304
	ds_read_b128 v[228:231], v204 offset:2368
	ds_read_b128 v[232:235], v204 offset:4608
	ds_read_b128 v[236:239], v204 offset:4672
	ds_read_b128 v[240:243], v204 offset:6912
	ds_read_b128 v[244:247], v204 offset:6976
	s_waitcnt lgkmcnt(9)
	v_mfma_f32_16x16x32_bf16 v[56:59], v[56:59], v[188:191], 0
	v_lshlrev_b32_e32 v60, 16, v54
	v_lshlrev_b32_e32 v188, 16, v55
	v_and_b32_e32 v189, 0xffff0000, v55
	s_waitcnt lgkmcnt(8)
	v_mfma_f32_16x16x32_bf16 v[54:57], v[184:187], v[192:195], v[56:59]
	v_mul_f32_e64 v14, v74, v14
	v_mul_f32_e64 v15, v75, v15
	v_pk_mul_f32 v[12:13], v[76:77], v[12:13]
	v_pk_mul_f32 v[10:11], v[74:75], v[10:11]
	v_add_co_u32_e32 v58, vcc, s66, v120
	v_pk_mul_f32 v[8:9], v[76:77], v[8:9]
	s_nop 1
	v_pk_mul_f32 v[56:57], v[94:95], v[56:57]
	v_pk_mul_f32 v[54:55], v[92:93], v[54:55]
	v_addc_co_u32_e32 v59, vcc, 0, v121, vcc
	v_cvt_pk_bf16_f32 v54, v54, v55
	v_cvt_pk_bf16_f32 v55, v56, v57
	ds_write_b64 v142, v[54:55]
	s_waitcnt lgkmcnt(0)
	s_barrier
; #define LAS __attribute__((address_space(3)))
; __device__ __forceinline__ unsigned pk2(float lo, float hi) { return pg8::cvt_pk_bf16(lo, hi); }
; __device__ __forceinline__ void retention_unit(LAS unsigned char* lds, const Ptrs& P, int b, int h, int tid) {
;     ...
;         if (n >= 1) {
; #pragma unroll
;             for (int it = 0; it < 4; ++it) { const int i = 16 * it + fr; const float mean = stat[i * 2], rstd = stat[i * 2 + 1]; const v2u sg = sgr[it];
;                 const f32x4 y = (op[it] - mean) * rstd * gng4 * (f32x4){bflo(sg.x), bfhi(sg.x), bflo(sg.y), bfhi(sg.y)};
;                 v2u pw; pw.x = pk2(y[0], y[1]); pw.y = pk2(y[2], y[3]);
;                 *(v2u*)(gol + ((size_t)(n - 1) * 64 + 16 * it) * 1024) = pw; }
;         }
;         if (n < 32) {
;             f32x4 o[4]; bf16x8 bst[2], bv[2];
; #pragma unroll
;             for (int ks = 0; ks < 2; ++ks) { bst[ks] = *(const LAS bf16x8*)(St + (16 * w + fr) * S72 + 32 * ks + 8 * fq); bv[ks] = tr_frag(bufc + ROFF_V, S144 * 2, w, ks, fq, fr); }
; #pragma unroll
;             for (int it = 0; it < 4; ++it) { o[it] = (f32x4){0.f, 0.f, 0.f, 0.f};
; #pragma unroll
;                 for (int ks = 0; ks < 2; ++ks) { const bf16x8 qf = *(const LAS bf16x8*)(Qs + (16 * it + fr) * S72 + 32 * ks + 8 * fq); o[it] = mfma16(bst[ks], qf, o[it]); }
;                 o[it] = o[it] * dqv[it];
; #pragma unroll
;                 for (int ks = 0; ks < 2; ++ks) { const bf16x8 sf = *(const LAS bf16x8*)(Ss + (16 * it + fr) * S72 + 32 * ks + 8 * fq); o[it] = mfma16(bv[ks], sf, o[it]); }
;             }
; #pragma unroll
;             for (int dt = 0; dt < 4; ++dt) { st[dt] = st[dt] * dch;
; #pragma unroll
;                 for (int ks = 0; ks < 2; ++ks) { const bf16x8 kf = tr_frag(bufc + ROFF_K2, S72 * 2, dt, ks, fq, fr); st[dt] = mfma16(kf, bv[ks], st[dt]); }
;                 v2u pw; pw.x = pk2(st[dt][0], st[dt][1]); pw.y = pk2(st[dt][2], st[dt][3]);
;                 *(LAS v2u*)(St + (16 * w + fr) * S72 + 16 * dt + 4 * fq) = pw; }
; #pragma unroll
;             for (int it = 0; it < 4; ++it) { const f32x4 v = o[it]; typedef float f32x2 __attribute__((ext_vector_type(2)));
;                 *(LAS f32x2*)(part + ((16 * it + fr) * 32 + w * 4 + fq) * 2) = (f32x2){(v[0] + v[1]) + (v[2] + v[3]), (v[0] * v[0] + v[1] * v[1]) + (v[2] * v[2] + v[3] * v[3])};
;                 op[it] = v; }
	ds_read2_b64 v[54:57], v143 offset1:16
	ds_read_b128 v[184:187], v137
	v_pk_mul_f32 v[6:7], v[74:75], v[6:7]
	v_pk_mul_f32 v[4:5], v[76:77], v[4:5]
	v_lshl_add_u64 v[110:111], v[110:111], 0, s[8:9]
	s_waitcnt lgkmcnt(1)
	v_sub_f32_e32 v41, v41, v54
	v_sub_f32_e32 v40, v40, v54
	v_sub_f32_e32 v43, v43, v54
	v_sub_f32_e32 v42, v42, v54
	v_pk_mul_f32 v[42:43], v[54:55], v[42:43] op_sel:[1,0]
	v_pk_mul_f32 v[40:41], v[54:55], v[40:41] op_sel:[1,0]
	v_pk_mul_f32 v[42:43], v[2:3], v[42:43]
	v_pk_mul_f32 v[40:41], v[0:1], v[40:41]
	v_pk_mul_f32 v[42:43], v[42:43], v[188:189]
	v_pk_mul_f32 v[40:41], v[40:41], v[60:61]
	v_sub_f32_e32 v45, v45, v56
	v_cvt_pk_bf16_f32 v40, v40, v41
	v_cvt_pk_bf16_f32 v41, v42, v43
	v_sub_f32_e32 v44, v44, v56
	global_store_dwordx2 v[58:59], v[40:41], off
	v_sub_f32_e32 v41, v47, v56
	v_sub_f32_e32 v40, v46, v56
	v_pk_mul_f32 v[40:41], v[56:57], v[40:41] op_sel:[1,0]
	v_pk_mul_f32 v[42:43], v[56:57], v[44:45] op_sel:[1,0]
	ds_read2_b64 v[54:57], v143 offset0:32 offset1:48
	v_pk_mul_f32 v[42:43], v[0:1], v[42:43]
	v_pk_mul_f32 v[40:41], v[2:3], v[40:41]
	v_lshlrev_b32_e32 v44, 16, v52
	v_and_b32_e32 v45, 0xffff0000, v52
	v_lshlrev_b32_e32 v46, 16, v53
	v_and_b32_e32 v47, 0xffff0000, v53
	v_pk_mul_f32 v[40:41], v[40:41], v[46:47]
	v_pk_mul_f32 v[42:43], v[42:43], v[44:45]
	ds_read_b128 v[188:191], v137 offset:64
	v_cvt_pk_bf16_f32 v42, v42, v43
	v_cvt_pk_bf16_f32 v43, v40, v41
	v_add_co_u32_e32 v40, vcc, s67, v120
	s_nop 0
	v_addc_co_u32_e32 v41, vcc, 0, v121, vcc
	global_store_dwordx2 v[40:41], v[42:43], off
	s_waitcnt lgkmcnt(1)
	v_sub_f32_e32 v41, v49, v54
	v_sub_f32_e32 v40, v48, v54
	v_sub_f32_e32 v43, v51, v54
	v_sub_f32_e32 v42, v50, v54
	v_pk_mul_f32 v[40:41], v[54:55], v[40:41] op_sel:[1,0]
	v_pk_mul_f32 v[192:193], v[54:55], v[42:43] op_sel:[1,0]
	v_pk_mul_f32 v[196:197], v[0:1], v[40:41]
	s_waitcnt lgkmcnt(0)
	v_mfma_f32_16x16x32_bf16 v[40:43], v[184:187], v[216:219], 0
	v_add3_u32 v48, s18, v162, v168
	ds_read_b64_tr_b16 v[58:59], v48 offset:27648
	ds_read_b64_tr_b16 v[60:61], v48 offset:28800
	ds_read_b64_tr_b16 v[52:53], v48 offset:36864
	ds_read_b64_tr_b16 v[54:55], v48 offset:38016
	ds_read_b128 v[48:51], v129
	v_pk_mul_f32 v[192:193], v[2:3], v[192:193]
	v_mfma_f32_16x16x32_bf16 v[40:43], v[188:191], v[220:223], v[40:43]
	ds_read_b128 v[44:47], v129 offset:64
	v_pk_mul_f32 v[122:123], v[192:193], v[122:123]
	ds_read_b128 v[192:195], v129 offset:2304
	v_lshl_add_u64 v[112:113], v[112:113], 0, s[12:13]
	v_lshl_add_u64 v[114:115], v[114:115], 0, s[14:15]
	s_nop 2
	v_pk_mul_f32 v[42:43], v[108:109], v[42:43]
	v_pk_mul_f32 v[40:41], v[90:91], v[40:41]
	s_cmp_lg_u32 s89, 30
	v_lshl_add_u64 v[116:117], v[116:117], 0, s[12:13]
	s_waitcnt lgkmcnt(2)
	v_mfma_f32_16x16x32_bf16 v[40:43], v[58:61], v[48:51], v[40:43]
	s_waitcnt lgkmcnt(1)
	v_mfma_f32_16x16x32_bf16 v[40:43], v[52:55], v[44:47], v[40:43]
	s_waitcnt lgkmcnt(0)
	v_mfma_f32_16x16x32_bf16 v[48:51], v[184:187], v[224:227], 0
	s_waitcnt lgkmcnt(0)
	v_mfma_f32_16x16x32_bf16 v[44:47], v[188:191], v[228:231], v[48:51]
	ds_read_b64_tr_b16 v[216:217], v212 offset:18432
	ds_read_b64_tr_b16 v[218:219], v212 offset:19008
	ds_read_b64_tr_b16 v[220:221], v212 offset:23040
	ds_read_b64_tr_b16 v[222:223], v212 offset:23616
	ds_read_b64_tr_b16 v[224:225], v212 offset:18464
	ds_read_b64_tr_b16 v[226:227], v212 offset:19040
	ds_read_b64_tr_b16 v[228:229], v212 offset:23072
	ds_read_b64_tr_b16 v[230:231], v212 offset:23648
	s_nop 5
	ds_read_b128 v[48:51], v129 offset:2368
	s_nop 0
	v_pk_mul_f32 v[46:47], v[106:107], v[46:47]
	v_pk_mul_f32 v[44:45], v[78:79], v[44:45]
	s_nop 1
	v_mfma_f32_16x16x32_bf16 v[44:47], v[58:61], v[192:195], v[44:47]
	v_mul_f32_e64 v192, v196, v200
	v_mul_f32_e64 v193, v197, v201
	ds_read_b128 v[200:203], v129 offset:4608
	v_cvt_pk_bf16_f32 v192, v192, v193
	s_waitcnt lgkmcnt(1)
	v_mfma_f32_16x16x32_bf16 v[44:47], v[52:55], v[48:51], v[44:47]
	v_cvt_pk_bf16_f32 v193, v122, v123
	v_add_co_u32_e32 v122, vcc, s68, v120
	v_sub_f32_e32 v197, v23, v56
	s_nop 0
	v_addc_co_u32_e32 v123, vcc, 0, v121, vcc
	global_store_dwordx2 v[122:123], v[192:193], off
	s_waitcnt lgkmcnt(0)
	v_mfma_f32_16x16x32_bf16 v[48:51], v[184:187], v[232:235], 0
	v_sub_f32_e32 v123, v21, v56
	v_sub_f32_e32 v122, v20, v56
	v_sub_f32_e32 v196, v22, v56
	s_waitcnt lgkmcnt(0)
	v_mfma_f32_16x16x32_bf16 v[48:51], v[188:191], v[236:239], v[48:51]
	ds_read_b64_tr_b16 v[232:233], v212 offset:18496
	ds_read_b64_tr_b16 v[234:235], v212 offset:19072
	ds_read_b64_tr_b16 v[236:237], v212 offset:23104
	ds_read_b64_tr_b16 v[238:239], v212 offset:23680
	ds_read_b128 v[192:195], v129 offset:4672
	v_pk_mul_f32 v[196:197], v[56:57], v[196:197] op_sel:[1,0]
	v_pk_mul_f32 v[56:57], v[56:57], v[122:123] op_sel:[1,0]
	v_pk_mul_f32 v[122:123], v[2:3], v[196:197]
	v_pk_mul_f32 v[56:57], v[0:1], v[56:57]
	s_nop 2
	v_pk_mul_f32 v[50:51], v[104:105], v[50:51]
	v_pk_mul_f32 v[48:49], v[86:87], v[48:49]
	v_lshlrev_b32_e32 v196, 16, v118
	v_and_b32_e32 v197, 0xffff0000, v118
	v_mfma_f32_16x16x32_bf16 v[48:51], v[58:61], v[200:203], v[48:51]
	s_waitcnt lgkmcnt(0)
	v_mfma_f32_16x16x32_bf16 v[16:19], v[216:219], v[58:61], v[16:19]
	s_waitcnt lgkmcnt(0)
	v_mfma_f32_16x16x32_bf16 v[16:19], v[220:223], v[52:55], v[16:19]
	v_mfma_f32_16x16x32_bf16 v[48:51], v[52:55], v[192:195], v[48:51]
	ds_read_b128 v[204:207], v129 offset:6912
	ds_read_b128 v[208:211], v129 offset:6976
	s_nop 2
	v_cvt_pk_bf16_f32 v20, v16, v17
	v_cvt_pk_bf16_f32 v21, v18, v19
	ds_write_b64 v132, v[20:21]
	s_waitcnt lgkmcnt(3)
	v_mfma_f32_16x16x32_bf16 v[184:187], v[184:187], v[240:243], 0
	s_waitcnt lgkmcnt(0)
; #define LAS __attribute__((address_space(3)))
; __device__ __forceinline__ unsigned pk2(float lo, float hi) { return pg8::cvt_pk_bf16(lo, hi); }
; __device__ __forceinline__ f32x4 mfma16(bf16x8 a, bf16x8 b, f32x4 c) { return __builtin_amdgcn_mfma_f32_16x16x32_bf16(a, b, c, 0, 0, 0); }
; __device__ __forceinline__ void retention_unit(LAS unsigned char* lds, const Ptrs& P, int b, int h, int tid) {
;     ...
;         if (n < 32) {
;             f32x4 o[4]; bf16x8 bst[2], bv[2];
; #pragma unroll
;             for (int ks = 0; ks < 2; ++ks) { bst[ks] = *(const LAS bf16x8*)(St + (16 * w + fr) * S72 + 32 * ks + 8 * fq); bv[ks] = tr_frag(bufc + ROFF_V, S144 * 2, w, ks, fq, fr); }
; #pragma unroll
;             for (int it = 0; it < 4; ++it) { o[it] = (f32x4){0.f, 0.f, 0.f, 0.f};
; #pragma unroll
;                 for (int ks = 0; ks < 2; ++ks) { const bf16x8 qf = *(const LAS bf16x8*)(Qs + (16 * it + fr) * S72 + 32 * ks + 8 * fq); o[it] = mfma16(bst[ks], qf, o[it]); }
;                 o[it] = o[it] * dqv[it];
; #pragma unroll
;                 for (int ks = 0; ks < 2; ++ks) { const bf16x8 sf = *(const LAS bf16x8*)(Ss + (16 * it + fr) * S72 + 32 * ks + 8 * fq); o[it] = mfma16(bv[ks], sf, o[it]); }
;             }
; #pragma unroll
;             for (int dt = 0; dt < 4; ++dt) { st[dt] = st[dt] * dch;
; #pragma unroll
;                 for (int ks = 0; ks < 2; ++ks) { const bf16x8 kf = tr_frag(bufc + ROFF_K2, S72 * 2, dt, ks, fq, fr); st[dt] = mfma16(kf, bv[ks], st[dt]); }
;                 v2u pw; pw.x = pk2(st[dt][0], st[dt][1]); pw.y = pk2(st[dt][2], st[dt][3]);
;                 *(LAS v2u*)(St + (16 * w + fr) * S72 + 16 * dt + 4 * fq) = pw; }
; #pragma unroll
;             for (int it = 0; it < 4; ++it) { const f32x4 v = o[it]; typedef float f32x2 __attribute__((ext_vector_type(2)));
;                 *(LAS f32x2*)(part + ((16 * it + fr) * 32 + w * 4 + fq) * 2) = (f32x2){(v[0] + v[1]) + (v[2] + v[3]), (v[0] * v[0] + v[1] * v[1]) + (v[2] * v[2] + v[3] * v[3])};
;                 op[it] = v; }
	v_mfma_f32_16x16x32_bf16 v[12:15], v[224:227], v[58:61], v[12:15]
	s_waitcnt lgkmcnt(0)
	v_mfma_f32_16x16x32_bf16 v[12:15], v[228:231], v[52:55], v[12:15]
	v_mfma_f32_16x16x32_bf16 v[184:187], v[188:191], v[244:247], v[184:187]
	ds_read_b64_tr_b16 v[240:241], v212 offset:18528
	ds_read_b64_tr_b16 v[242:243], v212 offset:19104
	ds_read_b64_tr_b16 v[244:245], v212 offset:23136
	ds_read_b64_tr_b16 v[246:247], v212 offset:23712
	s_nop 6
	v_cvt_pk_bf16_f32 v20, v12, v13
	v_cvt_pk_bf16_f32 v21, v14, v15
	ds_write_b64 v132, v[20:21] offset:32
	s_waitcnt lgkmcnt(0)
	v_mfma_f32_16x16x32_bf16 v[8:11], v[232:235], v[58:61], v[8:11]
	v_mul_f32_e64 v186, v96, v186
	v_mul_f32_e64 v187, v97, v187
	v_pk_mul_f32 v[184:185], v[88:89], v[184:185]
	v_lshlrev_b32_e32 v20, 16, v119
	s_waitcnt lgkmcnt(0)
	v_mfma_f32_16x16x32_bf16 v[8:11], v[236:239], v[52:55], v[8:11]
	v_and_b32_e32 v21, 0xffff0000, v119
	v_pk_mul_f32 v[20:21], v[122:123], v[20:21]
	v_mfma_f32_16x16x32_bf16 v[184:187], v[58:61], v[204:207], v[184:187]
	s_nop 4
	v_cvt_pk_bf16_f32 v22, v8, v9
	v_cvt_pk_bf16_f32 v23, v10, v11
	ds_write_b64 v132, v[22:23] offset:64
	v_pk_mul_f32 v[22:23], v[56:57], v[196:197]
	v_cvt_pk_bf16_f32 v57, v20, v21
	v_cvt_pk_bf16_f32 v56, v22, v23
	v_mfma_f32_16x16x32_bf16 v[20:23], v[52:55], v[208:211], v[184:187]
	s_nop 2
	s_waitcnt lgkmcnt(0)
	v_mfma_f32_16x16x32_bf16 v[4:7], v[240:243], v[58:61], v[4:7]
	v_add_co_u32_e32 v58, vcc, s69, v120
	s_waitcnt lgkmcnt(0)
	v_mfma_f32_16x16x32_bf16 v[4:7], v[244:247], v[52:55], v[4:7]
	v_addc_co_u32_e32 v59, vcc, 0, v121, vcc
	global_store_dwordx2 v[58:59], v[56:57], off
	v_mul_f32_e32 v55, v41, v41
	v_mul_f32_e32 v57, v42, v42
	s_nop 3
	v_cvt_pk_bf16_f32 v52, v4, v5
	v_cvt_pk_bf16_f32 v53, v6, v7
	ds_write_b64 v132, v[52:53] offset:96
	v_mul_f32_e32 v53, v40, v40
	v_mul_f32_e32 v59, v43, v43
	v_mov_b32_e32 v52, v40
	v_mov_b32_e32 v54, v41
	v_mov_b32_e32 v56, v42
	v_mov_b32_e32 v58, v43
	v_pk_add_f32 v[52:53], v[52:53], v[54:55]
	v_pk_add_f32 v[54:55], v[56:57], v[58:59]
	v_mul_f32_e32 v57, v46, v46
	v_pk_add_f32 v[52:53], v[52:53], v[54:55]
	ds_write_b64 v133, v[52:53]
	v_mul_f32_e32 v53, v44, v44
	v_mul_f32_e32 v55, v45, v45
	v_mul_f32_e32 v59, v47, v47
	v_mov_b32_e32 v52, v44
	v_mov_b32_e32 v54, v45
	v_mov_b32_e32 v56, v46
	v_mov_b32_e32 v58, v47
	v_pk_add_f32 v[52:53], v[52:53], v[54:55]
	v_pk_add_f32 v[54:55], v[56:57], v[58:59]
	v_mul_f32_e32 v57, v50, v50
	v_pk_add_f32 v[52:53], v[52:53], v[54:55]
	ds_write_b64 v134, v[52:53]
	v_mul_f32_e32 v53, v48, v48
	v_mul_f32_e32 v55, v49, v49
	v_mul_f32_e32 v59, v51, v51
	v_mov_b32_e32 v52, v48
	v_mov_b32_e32 v54, v49
	v_mov_b32_e32 v56, v50
	v_mov_b32_e32 v58, v51
	v_pk_add_f32 v[52:53], v[52:53], v[54:55]
	v_pk_add_f32 v[54:55], v[56:57], v[58:59]
	v_mul_f32_e32 v57, v22, v22
	v_pk_add_f32 v[52:53], v[52:53], v[54:55]
	ds_write_b64 v135, v[52:53]
	v_mul_f32_e32 v53, v20, v20
	v_mul_f32_e32 v55, v21, v21
	v_mul_f32_e32 v59, v23, v23
	v_mov_b32_e32 v52, v20
	v_mov_b32_e32 v54, v21
	v_mov_b32_e32 v56, v22
	v_mov_b32_e32 v58, v23
	v_pk_add_f32 v[52:53], v[52:53], v[54:55]
	v_pk_add_f32 v[54:55], v[56:57], v[58:59]
	s_nop 0
	v_pk_add_f32 v[52:53], v[52:53], v[54:55]
	ds_write_b64 v136, v[52:53]
	s_cbranch_scc0 .LBB0_660
; #define LAS __attribute__((address_space(3)))
; #define LBAR() do { asm volatile("s_waitcnt lgkmcnt(0)" ::: "memory"); __builtin_amdgcn_s_barrier(); asm volatile("" ::: "memory"); } while (0)
; __device__ __forceinline__ unsigned pk2(float lo, float hi) { return pg8::cvt_pk_bf16(lo, hi); }
; __device__ __forceinline__ void retention_unit(LAS unsigned char* lds, const Ptrs& P, int b, int h, int tid) {
;     ...
;     for (int n = 0; n <= 32; ++n) {
;         LAS unsigned char* bufc = lds + (n & 1) * RSET;
;         LAS bf16* Qs = (LAS bf16*)(bufc + ROFF_Q); LAS bf16* Ks = (LAS bf16*)(bufc + ROFF_K); LAS bf16* K2s = (LAS bf16*)(bufc + ROFF_K2); LAS bf16* Vs = (LAS bf16*)(bufc + ROFF_V);
;         if (n < 32) {
;             *(LAS v4u*)(Qs + lrow * S72 + lseg * 8) = rq; *(LAS v4u*)(Ks + lrow * S72 + lseg * 8) = rk;
;             v4u k2;
; #pragma unroll
;             for (int t = 0; t < 4; ++t) k2[t] = pk2(bflo(rk[t]) * dkey, bfhi(rk[t]) * dkey);
;             *(LAS v4u*)(K2s + lrow * S72 + lseg * 8) = k2;
;             *(LAS v4u*)(Vs + vrow0 * S144 + vseg * 8) = rv0; *(LAS v4u*)(Vs + (vrow0 + 32) * S144 + vseg * 8) = rv1;
;         }
;         if (n >= 1) {
; #pragma unroll
;             for (int it = 0; it < 4; ++it) sgr[it] = __builtin_nontemporal_load((const v2u*)(gsl + ((size_t)(n - 1) * 64 + 16 * it) * 512));
;         }
;         LBAR();
;         if (n + 1 < 32) { const size_t o4 = (size_t)(n + 1) * 64;
;             rq = __builtin_nontemporal_load((const v4u*)(gq + o4 * 256)); rk = __builtin_nontemporal_load((const v4u*)(gk + o4 * 256)); rv0 = __builtin_nontemporal_load((const v4u*)(gv + o4 * 512)); rv1 = __builtin_nontemporal_load((const v4u*)(gv + (o4 + 32) * 512)); }
;         if (n >= 1) {
;             const int row = tid >> 3, sub = tid & 7;
;             const f32x4 pa = *(const LAS f32x4*)(part + (row * 32 + sub * 4) * 2), pb = *(const LAS f32x4*)(part + (row * 32 + sub * 4) * 2 + 4);
;             float s1 = (pa[0] + pa[2]) + (pb[0] + pb[2]), s2 = (pa[1] + pa[3]) + (pb[1] + pb[3]);
; #pragma unroll
;             for (int x = 1; x < 8; x <<= 1) { s1 += __shfl_xor(s1, x); s2 += __shfl_xor(s2, x); }
;             if (sub == 0) { const float mean = s1 * (1.f / 128.f); float var = s2 * (1.f / 128.f) - mean * mean; var = var < 0.f ? 0.f : var;
;                 stat[row * 2] = mean; stat[row * 2 + 1] = __builtin_amdgcn_rsqf(var + 1e-5f); }
.LBB0_658:
	s_add_i32 s89, s89, 1
	s_bitcmp1_b32 s89, 0
	s_cselect_b32 s18, 0xb400, 0
	s_add_i32 s90, s18, 0
	v_add3_u32 v52, s90, v163, v72
	s_waitcnt vmcnt(7)
	ds_write_b128 v52, v[36:39]
	s_waitcnt vmcnt(6)
	ds_write_b128 v52, v[24:27] offset:9216
	v_lshlrev_b32_e32 v36, 16, v24
	v_and_b32_e32 v37, 0xffff0000, v24
	v_pk_mul_f32 v[36:37], v[102:103], v[36:37]
	v_add_u32_e32 v56, 0, v159
	v_cvt_pk_bf16_f32 v24, v36, v37
	v_lshlrev_b32_e32 v36, 16, v25
	v_and_b32_e32 v37, 0xffff0000, v25
	v_pk_mul_f32 v[36:37], v[102:103], v[36:37]
	v_add_u32_e32 v139, 0x1d400, v56
	v_cvt_pk_bf16_f32 v25, v36, v37
	v_lshlrev_b32_e32 v36, 16, v26
	v_and_b32_e32 v37, 0xffff0000, v26
	v_pk_mul_f32 v[36:37], v[102:103], v[36:37]
	v_and_b32_e32 v60, 64, v131
	v_cvt_pk_bf16_f32 v26, v36, v37
	v_lshlrev_b32_e32 v36, 16, v27
	v_and_b32_e32 v37, 0xffff0000, v27
	v_pk_mul_f32 v[36:37], v[102:103], v[36:37]
	v_add_u32_e32 v60, 64, v60
	v_cvt_pk_bf16_f32 v27, v36, v37
	ds_write_b128 v52, v[24:27] offset:18432
	v_add3_u32 v24, s90, v158, v84
	s_waitcnt vmcnt(5)
	ds_write_b128 v24, v[28:31] offset:27648
	s_waitcnt vmcnt(4)
	ds_write_b128 v24, v[32:35] offset:36864
	v_lshl_add_u64 v[24:25], s[26:27], 0, v[116:117]
	v_lshl_add_u64 v[24:25], v[24:25], 0, s[12:13]
	v_add_co_u32_e32 v26, vcc, s58, v24
	v_xor_b32_e32 v61, 1, v131
	s_nop 0
	v_addc_co_u32_e32 v27, vcc, 0, v25, vcc
	v_add_co_u32_e32 v28, vcc, s59, v24
	s_nop 1
	v_addc_co_u32_e32 v29, vcc, 0, v25, vcc
	v_add_co_u32_e32 v30, vcc, s60, v24
	s_nop 1
	v_addc_co_u32_e32 v31, vcc, 0, v25, vcc
	v_add_co_u32_e32 v24, vcc, s61, v24
	s_nop 1
	v_addc_co_u32_e32 v25, vcc, 0, v25, vcc
	v_mov_b32_e32 v54, v252
	v_mov_b32_e32 v55, v253
	v_mov_b32_e32 v52, v254
	v_mov_b32_e32 v53, v255
	v_mov_b32_e32 v122, v248
	v_mov_b32_e32 v123, v249
	v_mov_b32_e32 v118, v214
	v_mov_b32_e32 v119, v215
	global_load_dwordx2 v[252:253], v[26:27], off nt
	global_load_dwordx2 v[254:255], v[28:29], off nt
	global_load_dwordx2 v[248:249], v[30:31], off nt
	global_load_dwordx2 v[214:215], v[24:25], off nt
	v_lshl_add_u64 v[24:25], s[26:27], 0, v[110:111]
	v_add_co_u32_e32 v26, vcc, s62, v24
	v_lshl_add_u64 v[28:29], s[26:27], 0, v[112:113]
	s_nop 0
	v_addc_co_u32_e32 v27, vcc, 0, v25, vcc
	v_add_co_u32_e32 v24, vcc, s63, v24
	s_waitcnt lgkmcnt(0)
	s_barrier
	v_lshl_add_u32 v213, v155, 1, s90
	v_add_u32_e32 v75, v213, v62
	v_add_u32_e32 v213, v213, v179
	ds_read_b128 v[216:219], v213 offset:9216
	ds_read_b128 v[220:223], v213 offset:9280
	ds_read_b128 v[188:191], v75
	ds_read_b128 v[192:195], v75 offset:64
	s_nop 0
	v_addc_co_u32_e32 v25, vcc, 0, v25, vcc
	v_add_co_u32_e32 v30, vcc, s64, v28
	global_load_dwordx4 v[36:39], v[26:27], off nt
	s_nop 0
	global_load_dwordx4 v[24:27], v[24:25], off nt
	v_addc_co_u32_e32 v31, vcc, 0, v29, vcc
	v_add_co_u32_e32 v32, vcc, s65, v28
	s_nop 1
	v_addc_co_u32_e32 v33, vcc, 0, v29, vcc
	global_load_dwordx4 v[28:31], v[30:31], off nt
	s_nop 0
	global_load_dwordx4 v[32:35], v[32:33], off nt
	ds_read_b128 v[56:59], v139
	ds_read_b128 v[184:187], v139 offset:16
	v_cmp_lt_i32_e32 vcc, v61, v60
	s_waitcnt lgkmcnt(1)
	v_pk_add_f32 v[56:57], v[56:57], v[58:59]
	v_cndmask_b32_e32 v61, v131, v61, vcc
	s_waitcnt lgkmcnt(0)
	v_pk_add_f32 v[58:59], v[184:185], v[186:187]
	v_lshlrev_b32_e32 v138, 2, v61
	v_pk_add_f32 v[56:57], v[56:57], v[58:59]
	s_nop 1
	v_add_f32_dpp v56, v56, v56 quad_perm:[1,0,3,2] row_mask:0xf bank_mask:0xf
	v_add_f32_dpp v57, v57, v57 quad_perm:[1,0,3,2] row_mask:0xf bank_mask:0xf
	v_xor_b32_e32 v61, 2, v131
	v_cmp_lt_i32_e32 vcc, v61, v60
	s_nop 1
	v_cndmask_b32_e32 v61, v131, v61, vcc
	v_lshlrev_b32_e32 v140, 2, v61
	v_add_f32_dpp v56, v56, v56 quad_perm:[2,3,0,1] row_mask:0xf bank_mask:0xf
	v_add_f32_dpp v57, v57, v57 quad_perm:[2,3,0,1] row_mask:0xf bank_mask:0xf
	v_xor_b32_e32 v58, 4, v131
	v_cmp_lt_i32_e32 vcc, v58, v60
	s_nop 1
	v_cndmask_b32_e32 v58, v131, v58, vcc
	v_lshlrev_b32_e32 v141, 2, v58
	v_add_f32_dpp v56, v56, v56 row_half_mirror row_mask:0xf bank_mask:0xf
	v_add_f32_dpp v57, v57, v57 row_half_mirror row_mask:0xf bank_mask:0xf
	s_and_saveexec_b64 s[18:19], s[0:1]
	s_cbranch_execz .LBB0_657
	s_waitcnt lgkmcnt(0)
	v_add_u32_e32 v58, 0, v198
	v_pk_mul_f32 v[56:57], v[56:57], s[6:7] op_sel_hi:[1,0]
	v_add_u32_e32 v58, 0x21400, v58
	v_fma_f32 v57, -v56, v56, v57
	v_cmp_ngt_f32_e32 vcc, 0, v57
	s_nop 1
	v_cndmask_b32_e32 v57, 0, v57, vcc
	v_add_f32_e32 v57, 0x3727c5ac, v57
	v_rsq_f32_e32 v57, v57
	ds_write2_b32 v58, v56, v57 offset1:1
	s_branch .LBB0_657
